# baseline (speedup 1.0000x reference)
; DEVI float bflo(unsigned v) { return __uint_as_float(v << 16); }
; DEVI float bfhi(unsigned v) { return __uint_as_float(v & 0xffff0000u); }
; DEVI unsigned packbf(float a, float b) { fl2v v = {a, b}; bf2v r = __builtin_convertvector(v, bf2v); return __builtin_bit_cast(unsigned, r); }
; DEVI float sigm(float x) { return 1.f / (1.f + __expf(-x)); }
; DEVI void act_phase(int TID_, int BID_, PREF p, int g, int layer) {
;     ...
;     for (int t = 0; t < 4; ++t) { gr[t + 1] = *(const uint4*)(up + (size_t)t * 2 * DFF); vr[t] = *(const uint4*)(up + (size_t)t * 2 * DFF + DFF); }
;     gr[5] = ts0 + 4 < Ts ? *(const uint4*)(up + (size_t)4 * 2 * DFF) : make_uint4(0, 0, 0, 0);
;     float w0[8], w1[8], w2[8], bb[8];
; #pragma unroll
;     for (int k = 0; k < 8; k += 4) {
;       float4 a0 = *(const float4*)(cw + j + k), a1 = *(const float4*)(cw + DFF + j + k), a2 = *(const float4*)(cw + 2 * DFF + j + k),
;              a3 = *(const float4*)(cb + j + k);
;       w0[k] = a0.x; w0[k + 1] = a0.y; w0[k + 2] = a0.z; w0[k + 3] = a0.w;
;       w1[k] = a1.x; w1[k + 1] = a1.y; w1[k + 2] = a1.z; w1[k + 3] = a1.w;
;       w2[k] = a2.x; w2[k + 1] = a2.y; w2[k + 2] = a2.z; w2[k + 3] = a2.w;
;       bb[k] = a3.x; bb[k + 1] = a3.y; bb[k + 2] = a3.z; bb[k + 3] = a3.w;
;     }
; #pragma unroll
;     for (int t = 0; t < 4; ++t) {
;       const unsigned gm[4] = {gr[t].x, gr[t].y, gr[t].z, gr[t].w}, g0[4] = {gr[t + 1].x, gr[t + 1].y, gr[t + 1].z, gr[t + 1].w},
;                      gp[4] = {gr[t + 2].x, gr[t + 2].y, gr[t + 2].z, gr[t + 2].w}, va[4] = {vr[t].x, vr[t].y, vr[t].z, vr[t].w};
;       unsigned o[4];
; #pragma unroll
;       for (int k = 0; k < 4; ++k) {
;         float a = bflo(gm[k]) * w0[2 * k] + bflo(g0[k]) * w1[2 * k] + bflo(gp[k]) * w2[2 * k] + bb[2 * k];
;         float b = bfhi(gm[k]) * w0[2 * k + 1] + bfhi(g0[k]) * w1[2 * k + 1] + bfhi(gp[k]) * w2[2 * k + 1] + bb[2 * k + 1];
;         o[k] = packbf(a * sigm(a) * bflo(va[k]), b * sigm(b) * bfhi(va[k]));
.LBB0_71:
	s_or_b64 exec, exec, s[20:21]
	v_lshlrev_b32_e32 v196, 3, v10
	v_lshlrev_b64 v[8:9], 2, v[196:197]
	s_waitcnt vmcnt(12)
	v_lshl_add_u64 v[12:13], s[10:11], 0, v[8:9]
	s_waitcnt vmcnt(10)
	v_lshl_add_u64 v[16:17], s[14:15], 0, v[8:9]
	v_lshl_add_u64 v[20:21], s[16:17], 0, v[8:9]
	s_waitcnt vmcnt(8)
	v_lshl_add_u64 v[36:37], s[12:13], 0, v[8:9]
	global_load_dwordx4 v[8:11], v[12:13], off offset:16
	global_load_dwordx4 v[24:27], v[12:13], off
	s_nop 0
	global_load_dwordx4 v[12:15], v[16:17], off offset:16
	global_load_dwordx4 v[28:31], v[16:17], off
	s_nop 0
	global_load_dwordx4 v[16:19], v[20:21], off offset:16
	global_load_dwordx4 v[32:35], v[20:21], off
	s_nop 0
	global_load_dwordx4 v[20:23], v[36:37], off offset:16
	s_nop 0
	global_load_dwordx4 v[36:39], v[36:37], off
	s_waitcnt vmcnt(15)
	v_lshlrev_b32_e32 v76, 16, v60
	v_and_b32_e32 v77, 0xffff0000, v60
	v_lshlrev_b32_e32 v80, 16, v56
	v_and_b32_e32 v81, 0xffff0000, v56
	s_waitcnt vmcnt(13)
	v_lshlrev_b32_e32 v74, 16, v68
	v_and_b32_e32 v75, 0xffff0000, v68
	v_lshlrev_b32_e32 v82, 16, v64
	v_and_b32_e32 v83, 0xffff0000, v64
	v_lshlrev_b32_e32 v196, 1, v196
	v_lshl_add_u64 v[78:79], s[8:9], 0, v[196:197]
	v_mul_u32_u24_e32 v196, 0x5800, v86
	v_lshl_add_u64 v[72:73], v[72:73], 0, s[50:51]
	s_waitcnt vmcnt(4)
	v_pk_mul_f32 v[84:85], v[28:29], v[76:77]
	s_nop 0
	v_pk_fma_f32 v[80:81], v[24:25], v[80:81], v[84:85]
	s_waitcnt vmcnt(2)
	v_pk_fma_f32 v[80:81], v[32:33], v[74:75], v[80:81]
	s_waitcnt vmcnt(0)
	v_min_u32_e32 v218, 0x2bffff, v72
	v_mov_b32_e32 v220, 0xba2e8ba3
	v_mul_hi_u32 v219, v218, v220
	v_lshrrev_b32_e32 v219, 9, v219
	v_mul_u32_u24_e32 v220, 0x2c0, v219
	v_sub_u32_e32 v220, v218, v220
	v_lshlrev_b32_e32 v220, 4, v220
	v_mul_u32_u24_e32 v219, 0x16000, v219
	v_add_u32_e32 v218, v219, v220
	v_add_u32_e32 v219, 0x2c00, v218
	v_add_u32_e32 v220, 0x5800, v218
	v_add_u32_e32 v221, 0x8400, v218
	global_load_dwordx4 v[168:171], v218, s[6:7]
	global_load_dwordx4 v[168:171], v219, s[6:7]
	global_load_dwordx4 v[168:171], v220, s[6:7]
	global_load_dwordx4 v[168:171], v221, s[6:7]
	v_add_u32_e32 v219, 0xb000, v218
	v_add_u32_e32 v220, 0xdc00, v218
	v_add_u32_e32 v221, 0x10800, v218
	v_add_u32_e32 v222, 0x13400, v218
	global_load_dwordx4 v[168:171], v219, s[6:7]
	global_load_dwordx4 v[168:171], v220, s[6:7]
	global_load_dwordx4 v[168:171], v221, s[6:7]
	global_load_dwordx4 v[168:171], v222, s[6:7]
	v_pk_add_f32 v[80:81], v[80:81], v[36:37]
	s_nop 0
	v_mul_f32_e32 v56, 0xbfb8aa3b, v80
	v_exp_f32_e32 v84, v56
	v_mul_f32_e32 v56, 0xbfb8aa3b, v81
	v_exp_f32_e32 v85, v56
	s_nop 0
	v_pk_add_f32 v[84:85], v[84:85], 1.0 op_sel_hi:[1,0]
	s_nop 0
	v_div_scale_f32 v56, s[20:21], v85, v85, 1.0
	v_rcp_f32_e32 v60, v56
	s_nop 0
	v_fma_f32 v64, -v56, v60, 1.0
	v_fmac_f32_e32 v60, v64, v60
	v_div_scale_f32 v64, vcc, 1.0, v85, 1.0
	v_mul_f32_e32 v68, v64, v60
	v_fma_f32 v87, -v56, v68, v64
	v_fmac_f32_e32 v68, v87, v60
	v_fma_f32 v56, -v56, v68, v64
	v_div_fmas_f32 v56, v56, v60, v68
	v_div_fixup_f32 v85, v56, v85, 1.0
	v_div_scale_f32 v56, s[20:21], v84, v84, 1.0
	v_rcp_f32_e32 v60, v56
	s_nop 0
	v_fma_f32 v64, -v56, v60, 1.0
	v_fmac_f32_e32 v60, v64, v60
	v_div_scale_f32 v64, vcc, 1.0, v84, 1.0
	v_mul_f32_e32 v68, v64, v60
	v_fma_f32 v87, -v56, v68, v64
	v_fmac_f32_e32 v68, v87, v60
	v_fma_f32 v56, -v56, v68, v64
	v_div_fmas_f32 v56, v56, v60, v68
	v_div_fixup_f32 v84, v56, v84, 1.0
	v_pk_mul_f32 v[80:81], v[80:81], v[84:85]
	v_lshlrev_b32_e32 v60, 16, v65
	v_pk_mul_f32 v[80:81], v[80:81], v[82:83]
	v_lshlrev_b32_e32 v82, 16, v57
	v_cvt_pk_bf16_f32 v56, v80, v81
	v_lshlrev_b32_e32 v80, 16, v61
	v_and_b32_e32 v81, 0xffff0000, v61
	v_and_b32_e32 v83, 0xffff0000, v57
	v_and_b32_e32 v61, 0xffff0000, v65
	v_pk_mul_f32 v[64:65], v[30:31], v[80:81]
	v_lshlrev_b32_e32 v68, 16, v69
	v_and_b32_e32 v69, 0xffff0000, v69
	v_pk_fma_f32 v[64:65], v[26:27], v[82:83], v[64:65]
	s_nop 0
	v_pk_fma_f32 v[64:65], v[34:35], v[68:69], v[64:65]
	s_nop 0
	v_pk_add_f32 v[64:65], v[64:65], v[38:39]
	s_nop 0
	v_mul_f32_e32 v57, 0xbfb8aa3b, v64
	v_exp_f32_e32 v82, v57
	v_mul_f32_e32 v57, 0xbfb8aa3b, v65
	v_exp_f32_e32 v83, v57
	s_nop 0
	v_pk_add_f32 v[82:83], v[82:83], 1.0 op_sel_hi:[1,0]
	s_nop 0
	v_div_scale_f32 v57, s[20:21], v83, v83, 1.0
	v_rcp_f32_e32 v84, v57
	s_nop 0
	v_fma_f32 v85, -v57, v84, 1.0
	v_fmac_f32_e32 v84, v85, v84
	v_div_scale_f32 v85, vcc, 1.0, v83, 1.0
	v_mul_f32_e32 v87, v85, v84
	v_fma_f32 v88, -v57, v87, v85
	v_fmac_f32_e32 v87, v88, v84
	v_fma_f32 v57, -v57, v87, v85
	v_div_fmas_f32 v57, v57, v84, v87
	v_div_fixup_f32 v83, v57, v83, 1.0
	v_div_scale_f32 v57, s[20:21], v82, v82, 1.0
	v_rcp_f32_e32 v84, v57
	s_nop 0
	v_fma_f32 v85, -v57, v84, 1.0
	v_fmac_f32_e32 v84, v85, v84
	v_div_scale_f32 v85, vcc, 1.0, v82, 1.0
	v_mul_f32_e32 v87, v85, v84
	v_fma_f32 v88, -v57, v87, v85
	v_fmac_f32_e32 v87, v88, v84
	v_fma_f32 v57, -v57, v87, v85
	v_div_fmas_f32 v57, v57, v84, v87
	v_div_fixup_f32 v82, v57, v82, 1.0
	v_pk_mul_f32 v[64:65], v[64:65], v[82:83]
	v_lshlrev_b32_e32 v82, 16, v62
	v_pk_mul_f32 v[60:61], v[64:65], v[60:61]
	v_and_b32_e32 v83, 0xffff0000, v62
	v_cvt_pk_bf16_f32 v57, v60, v61
	v_lshlrev_b32_e32 v60, 16, v58
	v_and_b32_e32 v61, 0xffff0000, v58
	v_pk_mul_f32 v[88:89], v[12:13], v[82:83]
	v_lshlrev_b32_e32 v64, 16, v70
	v_and_b32_e32 v65, 0xffff0000, v70
	v_pk_fma_f32 v[60:61], v[8:9], v[60:61], v[88:89]
	v_lshlrev_b32_e32 v84, 16, v66
	v_pk_fma_f32 v[60:61], v[16:17], v[64:65], v[60:61]
	v_and_b32_e32 v85, 0xffff0000, v66
	v_pk_add_f32 v[60:61], v[60:61], v[20:21]
	s_nop 0
	v_mul_f32_e32 v58, 0xbfb8aa3b, v60
	v_exp_f32_e32 v88, v58
	v_mul_f32_e32 v58, 0xbfb8aa3b, v61
	v_exp_f32_e32 v89, v58
; DEVI float bflo(unsigned v) { return __uint_as_float(v << 16); }
; DEVI float bfhi(unsigned v) { return __uint_as_float(v & 0xffff0000u); }
; DEVI unsigned packbf(float a, float b) { fl2v v = {a, b}; bf2v r = __builtin_convertvector(v, bf2v); return __builtin_bit_cast(unsigned, r); }
; DEVI float sigm(float x) { return 1.f / (1.f + __expf(-x)); }
; DEVI void act_phase(int TID_, int BID_, PREF p, int g, int layer) {
;     ...
;       for (int k = 0; k < 4; ++k) {
;         float a = bflo(gm[k]) * w0[2 * k] + bflo(g0[k]) * w1[2 * k] + bflo(gp[k]) * w2[2 * k] + bb[2 * k];
;         float b = bfhi(gm[k]) * w0[2 * k + 1] + bfhi(g0[k]) * w1[2 * k + 1] + bfhi(gp[k]) * w2[2 * k + 1] + bb[2 * k + 1];
;         o[k] = packbf(a * sigm(a) * bflo(va[k]), b * sigm(b) * bfhi(va[k]));
;       }
;       *(uint4*)(act + (size_t)(tok0 + t) * DFF + j) = make_uint4(o[0], o[1], o[2], o[3]);
	s_nop 0
	v_pk_add_f32 v[88:89], v[88:89], 1.0 op_sel_hi:[1,0]
	s_nop 0
	v_div_scale_f32 v58, s[20:21], v89, v89, 1.0
	v_rcp_f32_e32 v62, v58
	s_nop 0
	v_fma_f32 v66, -v58, v62, 1.0
	v_fmac_f32_e32 v62, v66, v62
	v_div_scale_f32 v66, vcc, 1.0, v89, 1.0
	v_mul_f32_e32 v70, v66, v62
	v_fma_f32 v87, -v58, v70, v66
	v_fmac_f32_e32 v70, v87, v62
	v_fma_f32 v58, -v58, v70, v66
	v_div_fmas_f32 v58, v58, v62, v70
	v_div_fixup_f32 v89, v58, v89, 1.0
	v_div_scale_f32 v58, s[20:21], v88, v88, 1.0
	v_rcp_f32_e32 v62, v58
	s_nop 0
	v_fma_f32 v66, -v58, v62, 1.0
	v_fmac_f32_e32 v62, v66, v62
	v_div_scale_f32 v66, vcc, 1.0, v88, 1.0
	v_mul_f32_e32 v70, v66, v62
	v_fma_f32 v87, -v58, v70, v66
	v_fmac_f32_e32 v70, v87, v62
	v_fma_f32 v58, -v58, v70, v66
	v_div_fmas_f32 v58, v58, v62, v70
	v_div_fixup_f32 v88, v58, v88, 1.0
	v_pk_mul_f32 v[60:61], v[60:61], v[88:89]
	v_lshlrev_b32_e32 v62, 16, v71
	v_pk_mul_f32 v[60:61], v[60:61], v[84:85]
	v_lshlrev_b32_e32 v84, 16, v63
	v_and_b32_e32 v85, 0xffff0000, v63
	v_cvt_pk_bf16_f32 v58, v60, v61
	v_lshlrev_b32_e32 v60, 16, v59
	v_and_b32_e32 v61, 0xffff0000, v59
	v_and_b32_e32 v63, 0xffff0000, v71
	v_pk_mul_f32 v[70:71], v[14:15], v[84:85]
	v_lshlrev_b32_e32 v66, 16, v67
	v_pk_fma_f32 v[60:61], v[10:11], v[60:61], v[70:71]
	v_and_b32_e32 v67, 0xffff0000, v67
	v_pk_fma_f32 v[60:61], v[18:19], v[62:63], v[60:61]
	s_nop 0
	v_pk_add_f32 v[60:61], v[60:61], v[22:23]
	s_nop 0
	v_mul_f32_e32 v59, 0xbfb8aa3b, v60
	v_exp_f32_e32 v70, v59
	v_mul_f32_e32 v59, 0xbfb8aa3b, v61
	v_exp_f32_e32 v71, v59
	s_nop 0
	v_pk_add_f32 v[70:71], v[70:71], 1.0 op_sel_hi:[1,0]
	s_nop 0
	v_div_scale_f32 v59, s[20:21], v71, v71, 1.0
	v_rcp_f32_e32 v87, v59
	s_nop 0
	v_fma_f32 v88, -v59, v87, 1.0
	v_fmac_f32_e32 v87, v88, v87
	v_div_scale_f32 v88, vcc, 1.0, v71, 1.0
	v_mul_f32_e32 v89, v88, v87
	v_fma_f32 v90, -v59, v89, v88
	v_fmac_f32_e32 v89, v90, v87
	v_fma_f32 v59, -v59, v89, v88
	v_div_fmas_f32 v59, v59, v87, v89
	v_div_fixup_f32 v71, v59, v71, 1.0
	v_div_scale_f32 v59, s[20:21], v70, v70, 1.0
	v_rcp_f32_e32 v87, v59
	s_nop 0
	v_fma_f32 v88, -v59, v87, 1.0
	v_fmac_f32_e32 v87, v88, v87
	v_div_scale_f32 v88, vcc, 1.0, v70, 1.0
	v_mul_f32_e32 v89, v88, v87
	v_fma_f32 v90, -v59, v89, v88
	v_fmac_f32_e32 v89, v90, v87
	v_fma_f32 v59, -v59, v89, v88
	v_div_fmas_f32 v59, v59, v87, v89
	v_div_fixup_f32 v70, v59, v70, 1.0
	v_pk_mul_f32 v[60:61], v[60:61], v[70:71]
	s_nop 0
	v_pk_mul_f32 v[60:61], v[60:61], v[66:67]
	v_pk_mul_f32 v[66:67], v[28:29], v[74:75]
	v_cvt_pk_bf16_f32 v59, v60, v61
	v_lshl_add_u64 v[60:61], v[196:197], 1, v[78:79]
	global_store_dwordx4 v[60:61], v[56:59], off
	v_pk_fma_f32 v[66:67], v[24:25], v[76:77], v[66:67]
	s_nop 0
	v_lshlrev_b32_e32 v56, 16, v52
	v_and_b32_e32 v57, 0xffff0000, v52
	v_pk_fma_f32 v[66:67], v[32:33], v[56:57], v[66:67]
	v_lshlrev_b32_e32 v58, 16, v48
	v_pk_add_f32 v[66:67], v[66:67], v[36:37]
	v_and_b32_e32 v59, 0xffff0000, v48
	v_mul_f32_e32 v48, 0xbfb8aa3b, v66
	v_exp_f32_e32 v70, v48
	v_mul_f32_e32 v48, 0xbfb8aa3b, v67
	v_exp_f32_e32 v71, v48
	s_nop 0
	v_pk_add_f32 v[70:71], v[70:71], 1.0 op_sel_hi:[1,0]
	s_nop 0
	v_div_scale_f32 v48, s[20:21], v71, v71, 1.0
	v_rcp_f32_e32 v52, v48
	s_nop 0
	v_fma_f32 v76, -v48, v52, 1.0
	v_fmac_f32_e32 v52, v76, v52
	v_div_scale_f32 v76, vcc, 1.0, v71, 1.0
	v_mul_f32_e32 v77, v76, v52
	v_fma_f32 v78, -v48, v77, v76
	v_fmac_f32_e32 v77, v78, v52
	v_fma_f32 v48, -v48, v77, v76
	v_div_fmas_f32 v48, v48, v52, v77
	v_div_fixup_f32 v71, v48, v71, 1.0
	v_div_scale_f32 v48, s[20:21], v70, v70, 1.0
	v_rcp_f32_e32 v52, v48
	s_nop 0
	v_fma_f32 v76, -v48, v52, 1.0
	v_fmac_f32_e32 v52, v76, v52
	v_div_scale_f32 v76, vcc, 1.0, v70, 1.0
	v_mul_f32_e32 v77, v76, v52
	v_fma_f32 v78, -v48, v77, v76
	v_fmac_f32_e32 v77, v78, v52
	v_fma_f32 v48, -v48, v77, v76
	v_div_fmas_f32 v48, v48, v52, v77
	v_div_fixup_f32 v70, v48, v70, 1.0
	v_pk_mul_f32 v[66:67], v[66:67], v[70:71]
	v_lshlrev_b32_e32 v52, 16, v49
	v_pk_mul_f32 v[58:59], v[66:67], v[58:59]
	v_lshlrev_b32_e32 v66, 16, v53
	v_cvt_pk_bf16_f32 v48, v58, v59
	v_pk_mul_f32 v[58:59], v[30:31], v[68:69]
	v_and_b32_e32 v67, 0xffff0000, v53
	v_pk_fma_f32 v[58:59], v[26:27], v[80:81], v[58:59]
	v_and_b32_e32 v53, 0xffff0000, v49
	v_pk_fma_f32 v[58:59], v[34:35], v[66:67], v[58:59]
	s_nop 0
	v_pk_add_f32 v[58:59], v[58:59], v[38:39]
	s_nop 0
	v_mul_f32_e32 v49, 0xbfb8aa3b, v58
	v_exp_f32_e32 v70, v49
	v_mul_f32_e32 v49, 0xbfb8aa3b, v59
	v_exp_f32_e32 v71, v49
	s_nop 0
	v_pk_add_f32 v[70:71], v[70:71], 1.0 op_sel_hi:[1,0]
	s_nop 0
	v_div_scale_f32 v49, s[20:21], v71, v71, 1.0
	v_rcp_f32_e32 v76, v49
	s_nop 0
	v_fma_f32 v77, -v49, v76, 1.0
	v_fmac_f32_e32 v76, v77, v76
	v_div_scale_f32 v77, vcc, 1.0, v71, 1.0
	v_mul_f32_e32 v78, v77, v76
	v_fma_f32 v79, -v49, v78, v77
	v_fmac_f32_e32 v78, v79, v76
	v_fma_f32 v49, -v49, v78, v77
	v_div_fmas_f32 v49, v49, v76, v78
	v_div_fixup_f32 v71, v49, v71, 1.0
	v_div_scale_f32 v49, s[20:21], v70, v70, 1.0
	v_rcp_f32_e32 v76, v49
	s_nop 0
	v_fma_f32 v77, -v49, v76, 1.0
	v_fmac_f32_e32 v76, v77, v76
	v_div_scale_f32 v77, vcc, 1.0, v70, 1.0
	v_mul_f32_e32 v78, v77, v76
	v_fma_f32 v79, -v49, v78, v77
	v_fmac_f32_e32 v78, v79, v76
	v_fma_f32 v49, -v49, v78, v77
	v_div_fmas_f32 v49, v49, v76, v78
	v_div_fixup_f32 v70, v49, v70, 1.0
	v_pk_mul_f32 v[58:59], v[58:59], v[70:71]
	v_pk_mul_f32 v[70:71], v[12:13], v[64:65]
	v_pk_mul_f32 v[52:53], v[58:59], v[52:53]
	v_lshlrev_b32_e32 v58, 16, v54
	v_and_b32_e32 v59, 0xffff0000, v54
	v_pk_fma_f32 v[70:71], v[8:9], v[82:83], v[70:71]
	v_cvt_pk_bf16_f32 v49, v52, v53
	v_pk_fma_f32 v[70:71], v[16:17], v[58:59], v[70:71]
	v_lshlrev_b32_e32 v52, 16, v50
; DEVI float bflo(unsigned v) { return __uint_as_float(v << 16); }
; DEVI float bfhi(unsigned v) { return __uint_as_float(v & 0xffff0000u); }
; DEVI unsigned packbf(float a, float b) { fl2v v = {a, b}; bf2v r = __builtin_convertvector(v, bf2v); return __builtin_bit_cast(unsigned, r); }
; DEVI float sigm(float x) { return 1.f / (1.f + __expf(-x)); }
; DEVI void act_phase(int TID_, int BID_, PREF p, int g, int layer) {
;     ...
;       for (int k = 0; k < 4; ++k) {
;         float a = bflo(gm[k]) * w0[2 * k] + bflo(g0[k]) * w1[2 * k] + bflo(gp[k]) * w2[2 * k] + bb[2 * k];
;         float b = bfhi(gm[k]) * w0[2 * k + 1] + bfhi(g0[k]) * w1[2 * k + 1] + bfhi(gp[k]) * w2[2 * k + 1] + bb[2 * k + 1];
;         o[k] = packbf(a * sigm(a) * bflo(va[k]), b * sigm(b) * bfhi(va[k]));
;       }
;       *(uint4*)(act + (size_t)(tok0 + t) * DFF + j) = make_uint4(o[0], o[1], o[2], o[3]);
	v_pk_add_f32 v[70:71], v[70:71], v[20:21]
	v_and_b32_e32 v53, 0xffff0000, v50
	v_mul_f32_e32 v50, 0xbfb8aa3b, v70
	v_exp_f32_e32 v76, v50
	v_mul_f32_e32 v50, 0xbfb8aa3b, v71
	v_exp_f32_e32 v77, v50
	s_nop 0
	v_pk_add_f32 v[76:77], v[76:77], 1.0 op_sel_hi:[1,0]
	s_nop 0
	v_div_scale_f32 v50, s[20:21], v77, v77, 1.0
	v_rcp_f32_e32 v54, v50
	s_nop 0
	v_fma_f32 v78, -v50, v54, 1.0
	v_fmac_f32_e32 v54, v78, v54
	v_div_scale_f32 v78, vcc, 1.0, v77, 1.0
	v_mul_f32_e32 v79, v78, v54
	v_fma_f32 v80, -v50, v79, v78
	v_fmac_f32_e32 v79, v80, v54
	v_fma_f32 v50, -v50, v79, v78
	v_div_fmas_f32 v50, v50, v54, v79
	v_div_fixup_f32 v77, v50, v77, 1.0
	v_div_scale_f32 v50, s[20:21], v76, v76, 1.0
	v_rcp_f32_e32 v54, v50
	s_nop 0
	v_fma_f32 v78, -v50, v54, 1.0
	v_fmac_f32_e32 v54, v78, v54
	v_div_scale_f32 v78, vcc, 1.0, v76, 1.0
	v_mul_f32_e32 v79, v78, v54
	v_fma_f32 v80, -v50, v79, v78
	v_fmac_f32_e32 v79, v80, v54
	v_fma_f32 v50, -v50, v79, v78
	v_div_fmas_f32 v50, v50, v54, v79
	v_div_fixup_f32 v76, v50, v76, 1.0
	v_pk_mul_f32 v[70:71], v[70:71], v[76:77]
	v_lshlrev_b32_e32 v54, 16, v51
	v_pk_mul_f32 v[52:53], v[70:71], v[52:53]
	v_pk_mul_f32 v[70:71], v[14:15], v[62:63]
	v_cvt_pk_bf16_f32 v50, v52, v53
	v_lshlrev_b32_e32 v52, 16, v55
	v_and_b32_e32 v53, 0xffff0000, v55
	v_pk_fma_f32 v[70:71], v[10:11], v[84:85], v[70:71]
	v_and_b32_e32 v55, 0xffff0000, v51
	v_pk_fma_f32 v[70:71], v[18:19], v[52:53], v[70:71]
	s_nop 0
	v_pk_add_f32 v[70:71], v[70:71], v[22:23]
	s_nop 0
	v_mul_f32_e32 v51, 0xbfb8aa3b, v70
	v_exp_f32_e32 v76, v51
	v_mul_f32_e32 v51, 0xbfb8aa3b, v71
	v_exp_f32_e32 v77, v51
	s_nop 0
	v_pk_add_f32 v[76:77], v[76:77], 1.0 op_sel_hi:[1,0]
	s_nop 0
	v_div_scale_f32 v51, s[20:21], v77, v77, 1.0
	v_rcp_f32_e32 v78, v51
	s_nop 0
	v_fma_f32 v79, -v51, v78, 1.0
	v_fmac_f32_e32 v78, v79, v78
	v_div_scale_f32 v79, vcc, 1.0, v77, 1.0
	v_mul_f32_e32 v80, v79, v78
	v_fma_f32 v81, -v51, v80, v79
	v_fmac_f32_e32 v80, v81, v78
	v_fma_f32 v51, -v51, v80, v79
	v_div_fmas_f32 v51, v51, v78, v80
	v_div_fixup_f32 v77, v51, v77, 1.0
	v_div_scale_f32 v51, s[20:21], v76, v76, 1.0
	v_rcp_f32_e32 v78, v51
	s_movk_i32 s20, 0x2000
	v_fma_f32 v79, -v51, v78, 1.0
	v_fmac_f32_e32 v78, v79, v78
	v_div_scale_f32 v79, vcc, 1.0, v76, 1.0
	v_mul_f32_e32 v80, v79, v78
	v_fma_f32 v81, -v51, v80, v79
	v_fmac_f32_e32 v80, v81, v78
	v_fma_f32 v51, -v51, v80, v79
	v_div_fmas_f32 v51, v51, v78, v80
	v_div_fixup_f32 v76, v51, v76, 1.0
	v_pk_mul_f32 v[70:71], v[70:71], v[76:77]
	s_nop 0
	v_pk_mul_f32 v[54:55], v[70:71], v[54:55]
	s_nop 0
	v_cvt_pk_bf16_f32 v51, v54, v55
	v_add_co_u32_e32 v54, vcc, s20, v60
	s_nop 1
	v_addc_co_u32_e32 v55, vcc, 0, v61, vcc
	global_store_dwordx4 v[54:55], v[48:51], off offset:3072
	v_lshlrev_b32_e32 v54, 16, v44
	v_and_b32_e32 v55, 0xffff0000, v44
	v_pk_mul_f32 v[50:51], v[28:29], v[56:57]
	v_lshlrev_b32_e32 v48, 16, v40
	v_pk_fma_f32 v[50:51], v[24:25], v[74:75], v[50:51]
	v_and_b32_e32 v49, 0xffff0000, v40
	v_pk_fma_f32 v[50:51], v[32:33], v[54:55], v[50:51]
	v_pk_mul_f32 v[28:29], v[28:29], v[54:55]
	v_pk_add_f32 v[50:51], v[50:51], v[36:37]
	v_pk_fma_f32 v[24:25], v[24:25], v[56:57], v[28:29]
	v_mul_f32_e32 v40, 0xbfb8aa3b, v50
	v_exp_f32_e32 v70, v40
	v_mul_f32_e32 v40, 0xbfb8aa3b, v51
	v_exp_f32_e32 v71, v40
	v_lshlrev_b32_e32 v28, 16, v0
	v_and_b32_e32 v29, 0xffff0000, v0
	v_pk_fma_f32 v[24:25], v[32:33], v[28:29], v[24:25]
	v_pk_add_f32 v[70:71], v[70:71], 1.0 op_sel_hi:[1,0]
	v_pk_add_f32 v[24:25], v[24:25], v[36:37]
	v_div_scale_f32 v40, s[20:21], v71, v71, 1.0
	v_rcp_f32_e32 v44, v40
	v_mul_f32_e32 v0, 0xbfb8aa3b, v24
	v_exp_f32_e32 v28, v0
	v_mul_f32_e32 v0, 0xbfb8aa3b, v25
	v_fma_f32 v74, -v40, v44, 1.0
	v_fmac_f32_e32 v44, v74, v44
	v_div_scale_f32 v74, vcc, 1.0, v71, 1.0
	v_mul_f32_e32 v75, v74, v44
	v_fma_f32 v76, -v40, v75, v74
	v_fmac_f32_e32 v75, v76, v44
	v_fma_f32 v40, -v40, v75, v74
	v_div_fmas_f32 v40, v40, v44, v75
	v_div_fixup_f32 v71, v40, v71, 1.0
	v_div_scale_f32 v40, s[20:21], v70, v70, 1.0
	v_rcp_f32_e32 v44, v40
	v_exp_f32_e32 v29, v0
	v_fma_f32 v74, -v40, v44, 1.0
	v_fmac_f32_e32 v44, v74, v44
	v_div_scale_f32 v74, vcc, 1.0, v70, 1.0
	v_mul_f32_e32 v75, v74, v44
	v_fma_f32 v76, -v40, v75, v74
	v_fmac_f32_e32 v75, v76, v44
	v_fma_f32 v40, -v40, v75, v74
	v_div_fmas_f32 v40, v40, v44, v75
	v_div_fixup_f32 v70, v40, v70, 1.0
	v_pk_mul_f32 v[50:51], v[50:51], v[70:71]
	v_lshlrev_b32_e32 v44, 16, v41
	v_pk_mul_f32 v[48:49], v[50:51], v[48:49]
	v_lshlrev_b32_e32 v50, 16, v45
	v_cvt_pk_bf16_f32 v40, v48, v49
	v_pk_mul_f32 v[48:49], v[30:31], v[66:67]
	v_and_b32_e32 v51, 0xffff0000, v45
	v_pk_fma_f32 v[48:49], v[26:27], v[68:69], v[48:49]
	v_and_b32_e32 v45, 0xffff0000, v41
	v_pk_fma_f32 v[48:49], v[34:35], v[50:51], v[48:49]
	v_pk_add_f32 v[28:29], v[28:29], 1.0 op_sel_hi:[1,0]
	v_pk_add_f32 v[48:49], v[48:49], v[38:39]
	s_nop 0
	v_mul_f32_e32 v41, 0xbfb8aa3b, v48
	v_exp_f32_e32 v68, v41
	v_mul_f32_e32 v41, 0xbfb8aa3b, v49
	v_exp_f32_e32 v69, v41
	s_nop 0
	v_pk_add_f32 v[68:69], v[68:69], 1.0 op_sel_hi:[1,0]
	s_nop 0
	v_div_scale_f32 v41, s[20:21], v69, v69, 1.0
	v_rcp_f32_e32 v70, v41
	s_nop 0
	v_fma_f32 v71, -v41, v70, 1.0
	v_fmac_f32_e32 v70, v71, v70
	v_div_scale_f32 v71, vcc, 1.0, v69, 1.0
	v_mul_f32_e32 v74, v71, v70
	v_fma_f32 v75, -v41, v74, v71
	v_fmac_f32_e32 v74, v75, v70
	v_fma_f32 v41, -v41, v74, v71
	v_div_fmas_f32 v41, v41, v70, v74
	v_div_fixup_f32 v69, v41, v69, 1.0
	v_div_scale_f32 v41, s[20:21], v68, v68, 1.0
	v_rcp_f32_e32 v70, v41
	s_nop 0
	v_fma_f32 v71, -v41, v70, 1.0
	v_fmac_f32_e32 v70, v71, v70
	v_div_scale_f32 v71, vcc, 1.0, v68, 1.0
	v_mul_f32_e32 v74, v71, v70
	v_fma_f32 v75, -v41, v74, v71
; DEVI float bflo(unsigned v) { return __uint_as_float(v << 16); }
; DEVI float bfhi(unsigned v) { return __uint_as_float(v & 0xffff0000u); }
; DEVI unsigned packbf(float a, float b) { fl2v v = {a, b}; bf2v r = __builtin_convertvector(v, bf2v); return __builtin_bit_cast(unsigned, r); }
; DEVI float sigm(float x) { return 1.f / (1.f + __expf(-x)); }
; DEVI void act_phase(int TID_, int BID_, PREF p, int g, int layer) {
;     ...
;       for (int k = 0; k < 4; ++k) {
;         float a = bflo(gm[k]) * w0[2 * k] + bflo(g0[k]) * w1[2 * k] + bflo(gp[k]) * w2[2 * k] + bb[2 * k];
;         float b = bfhi(gm[k]) * w0[2 * k + 1] + bfhi(g0[k]) * w1[2 * k + 1] + bfhi(gp[k]) * w2[2 * k + 1] + bb[2 * k + 1];
;         o[k] = packbf(a * sigm(a) * bflo(va[k]), b * sigm(b) * bfhi(va[k]));
;       }
;       *(uint4*)(act + (size_t)(tok0 + t) * DFF + j) = make_uint4(o[0], o[1], o[2], o[3]);
	v_fmac_f32_e32 v74, v75, v70
	v_fma_f32 v41, -v41, v74, v71
	v_div_fmas_f32 v41, v41, v70, v74
	v_div_fixup_f32 v68, v41, v68, 1.0
	v_pk_mul_f32 v[48:49], v[48:49], v[68:69]
	v_pk_mul_f32 v[68:69], v[12:13], v[58:59]
	v_pk_mul_f32 v[44:45], v[48:49], v[44:45]
	v_lshlrev_b32_e32 v48, 16, v46
	v_and_b32_e32 v49, 0xffff0000, v46
	v_pk_fma_f32 v[64:65], v[8:9], v[64:65], v[68:69]
	v_cvt_pk_bf16_f32 v41, v44, v45
	v_pk_fma_f32 v[64:65], v[16:17], v[48:49], v[64:65]
	v_lshlrev_b32_e32 v44, 16, v42
	v_pk_add_f32 v[64:65], v[64:65], v[20:21]
	v_and_b32_e32 v45, 0xffff0000, v42
	v_mul_f32_e32 v42, 0xbfb8aa3b, v64
	v_exp_f32_e32 v68, v42
	v_mul_f32_e32 v42, 0xbfb8aa3b, v65
	v_exp_f32_e32 v69, v42
	v_pk_mul_f32 v[12:13], v[12:13], v[48:49]
	v_pk_add_f32 v[68:69], v[68:69], 1.0 op_sel_hi:[1,0]
	s_nop 0
	v_div_scale_f32 v42, s[20:21], v69, v69, 1.0
	v_rcp_f32_e32 v46, v42
	v_pk_fma_f32 v[8:9], v[8:9], v[58:59], v[12:13]
	v_lshlrev_b32_e32 v12, 16, v2
	v_and_b32_e32 v13, 0xffff0000, v2
	v_fma_f32 v70, -v42, v46, 1.0
	v_fmac_f32_e32 v46, v70, v46
	v_div_scale_f32 v70, vcc, 1.0, v69, 1.0
	v_mul_f32_e32 v71, v70, v46
	v_fma_f32 v74, -v42, v71, v70
	v_fmac_f32_e32 v71, v74, v46
	v_fma_f32 v42, -v42, v71, v70
	v_div_fmas_f32 v42, v42, v46, v71
	v_div_fixup_f32 v69, v42, v69, 1.0
	v_div_scale_f32 v42, s[20:21], v68, v68, 1.0
	v_rcp_f32_e32 v46, v42
	v_pk_fma_f32 v[8:9], v[16:17], v[12:13], v[8:9]
	v_fma_f32 v70, -v42, v46, 1.0
	v_fmac_f32_e32 v46, v70, v46
	v_div_scale_f32 v70, vcc, 1.0, v68, 1.0
	v_mul_f32_e32 v71, v70, v46
	v_fma_f32 v74, -v42, v71, v70
	v_fmac_f32_e32 v71, v74, v46
	v_fma_f32 v42, -v42, v71, v70
	v_div_fmas_f32 v42, v42, v46, v71
	v_div_fixup_f32 v68, v42, v68, 1.0
	v_pk_mul_f32 v[64:65], v[64:65], v[68:69]
	v_lshlrev_b32_e32 v46, 16, v43
	v_pk_mul_f32 v[44:45], v[64:65], v[44:45]
	v_pk_mul_f32 v[64:65], v[14:15], v[52:53]
	v_cvt_pk_bf16_f32 v42, v44, v45
	v_lshlrev_b32_e32 v44, 16, v47
	v_and_b32_e32 v45, 0xffff0000, v47
	v_pk_fma_f32 v[62:63], v[10:11], v[62:63], v[64:65]
	v_and_b32_e32 v47, 0xffff0000, v43
	v_pk_fma_f32 v[62:63], v[18:19], v[44:45], v[62:63]
	v_pk_add_f32 v[8:9], v[8:9], v[20:21]
	v_pk_add_f32 v[62:63], v[62:63], v[22:23]
	v_mul_f32_e32 v2, 0xbfb8aa3b, v8
	v_mul_f32_e32 v43, 0xbfb8aa3b, v62
	v_exp_f32_e32 v64, v43
	v_mul_f32_e32 v43, 0xbfb8aa3b, v63
	v_exp_f32_e32 v65, v43
	v_exp_f32_e32 v12, v2
	v_mul_f32_e32 v2, 0xbfb8aa3b, v9
	v_exp_f32_e32 v13, v2
	v_pk_add_f32 v[64:65], v[64:65], 1.0 op_sel_hi:[1,0]
	v_pk_add_f32 v[12:13], v[12:13], 1.0 op_sel_hi:[1,0]
	v_div_scale_f32 v43, s[20:21], v65, v65, 1.0
	v_rcp_f32_e32 v68, v43
	s_nop 0
	v_fma_f32 v69, -v43, v68, 1.0
	v_fmac_f32_e32 v68, v69, v68
	v_div_scale_f32 v69, vcc, 1.0, v65, 1.0
	v_mul_f32_e32 v70, v69, v68
	v_fma_f32 v71, -v43, v70, v69
	v_fmac_f32_e32 v70, v71, v68
	v_fma_f32 v43, -v43, v70, v69
	v_div_fmas_f32 v43, v43, v68, v70
	v_div_fixup_f32 v65, v43, v65, 1.0
	v_div_scale_f32 v43, s[20:21], v64, v64, 1.0
	v_rcp_f32_e32 v68, v43
	s_movk_i32 s20, 0x5000
	v_fma_f32 v69, -v43, v68, 1.0
	v_fmac_f32_e32 v68, v69, v68
	v_div_scale_f32 v69, vcc, 1.0, v64, 1.0
	v_mul_f32_e32 v70, v69, v68
	v_fma_f32 v71, -v43, v70, v69
	v_fmac_f32_e32 v70, v71, v68
	v_fma_f32 v43, -v43, v70, v69
	v_div_fmas_f32 v43, v43, v68, v70
	v_div_fixup_f32 v64, v43, v64, 1.0
	v_pk_mul_f32 v[62:63], v[62:63], v[64:65]
	s_nop 0
	v_pk_mul_f32 v[46:47], v[62:63], v[46:47]
	s_nop 0
	v_cvt_pk_bf16_f32 v43, v46, v47
	v_add_co_u32_e32 v46, vcc, s20, v60
	v_div_scale_f32 v0, s[20:21], v29, v29, 1.0
	s_nop 0
	v_addc_co_u32_e32 v47, vcc, 0, v61, vcc
	global_store_dwordx4 v[46:47], v[40:43], off offset:2048
	v_div_scale_f32 v2, s[20:21], v13, v13, 1.0
	s_nop 0
	v_lshlrev_b32_e32 v40, 16, v4
	v_and_b32_e32 v41, 0xffff0000, v4
	v_rcp_f32_e32 v4, v0
	s_nop 0
	v_fma_f32 v32, -v0, v4, 1.0
	v_fmac_f32_e32 v4, v32, v4
	v_div_scale_f32 v32, vcc, 1.0, v29, 1.0
	v_mul_f32_e32 v33, v32, v4
	v_fma_f32 v36, -v0, v33, v32
	v_fmac_f32_e32 v33, v36, v4
	v_fma_f32 v0, -v0, v33, v32
	v_div_fmas_f32 v0, v0, v4, v33
	v_div_fixup_f32 v29, v0, v29, 1.0
	v_div_scale_f32 v0, s[20:21], v28, v28, 1.0
	v_rcp_f32_e32 v4, v0
	s_nop 0
	v_fma_f32 v32, -v0, v4, 1.0
	v_fmac_f32_e32 v4, v32, v4
	v_div_scale_f32 v32, vcc, 1.0, v28, 1.0
; DEVI float bflo(unsigned v) { return __uint_as_float(v << 16); }
; DEVI float bfhi(unsigned v) { return __uint_as_float(v & 0xffff0000u); }
; DEVI unsigned packbf(float a, float b) { fl2v v = {a, b}; bf2v r = __builtin_convertvector(v, bf2v); return __builtin_bit_cast(unsigned, r); }
; DEVI float sigm(float x) { return 1.f / (1.f + __expf(-x)); }
; DEVI void act_phase(int TID_, int BID_, PREF p, int g, int layer) {
;     ...
;   for (size_t idx = (size_t)BID_ * 512 + TID_; idx < total; idx += (size_t)gridDim.x * 512) {
;     ...
;       for (int k = 0; k < 4; ++k) {
;         float a = bflo(gm[k]) * w0[2 * k] + bflo(g0[k]) * w1[2 * k] + bflo(gp[k]) * w2[2 * k] + bb[2 * k];
;         float b = bfhi(gm[k]) * w0[2 * k + 1] + bfhi(g0[k]) * w1[2 * k + 1] + bfhi(gp[k]) * w2[2 * k + 1] + bb[2 * k + 1];
;         o[k] = packbf(a * sigm(a) * bflo(va[k]), b * sigm(b) * bfhi(va[k]));
;       }
;       *(uint4*)(act + (size_t)(tok0 + t) * DFF + j) = make_uint4(o[0], o[1], o[2], o[3]);
;     }
	v_mul_f32_e32 v33, v32, v4
	v_fma_f32 v36, -v0, v33, v32
	v_fmac_f32_e32 v33, v36, v4
	v_fma_f32 v0, -v0, v33, v32
	v_div_fmas_f32 v0, v0, v4, v33
	v_div_fixup_f32 v28, v0, v28, 1.0
	v_pk_mul_f32 v[24:25], v[24:25], v[28:29]
	v_lshlrev_b32_e32 v4, 16, v5
	v_pk_mul_f32 v[24:25], v[24:25], v[40:41]
	v_and_b32_e32 v5, 0xffff0000, v5
	v_cvt_pk_bf16_f32 v0, v24, v25
	v_pk_mul_f32 v[24:25], v[30:31], v[50:51]
	s_nop 0
	v_pk_fma_f32 v[24:25], v[26:27], v[66:67], v[24:25]
	v_lshlrev_b32_e32 v26, 16, v1
	v_and_b32_e32 v27, 0xffff0000, v1
	v_pk_fma_f32 v[24:25], v[34:35], v[26:27], v[24:25]
	s_nop 0
	v_pk_add_f32 v[24:25], v[24:25], v[38:39]
	s_nop 0
	v_mul_f32_e32 v1, 0xbfb8aa3b, v24
	v_exp_f32_e32 v26, v1
	v_mul_f32_e32 v1, 0xbfb8aa3b, v25
	v_exp_f32_e32 v27, v1
	s_nop 0
	v_pk_add_f32 v[26:27], v[26:27], 1.0 op_sel_hi:[1,0]
	s_nop 0
	v_div_scale_f32 v1, s[20:21], v27, v27, 1.0
	v_rcp_f32_e32 v28, v1
	s_nop 0
	v_fma_f32 v29, -v1, v28, 1.0
	v_fmac_f32_e32 v28, v29, v28
	v_div_scale_f32 v29, vcc, 1.0, v27, 1.0
	v_mul_f32_e32 v30, v29, v28
	v_fma_f32 v31, -v1, v30, v29
	v_fmac_f32_e32 v30, v31, v28
	v_fma_f32 v1, -v1, v30, v29
	v_div_fmas_f32 v1, v1, v28, v30
	v_div_fixup_f32 v27, v1, v27, 1.0
	v_div_scale_f32 v1, s[20:21], v26, v26, 1.0
	v_rcp_f32_e32 v28, v1
	s_nop 0
	v_fma_f32 v29, -v1, v28, 1.0
	v_fmac_f32_e32 v28, v29, v28
	v_div_scale_f32 v29, vcc, 1.0, v26, 1.0
	v_mul_f32_e32 v30, v29, v28
	v_fma_f32 v31, -v1, v30, v29
	v_fmac_f32_e32 v30, v31, v28
	v_fma_f32 v1, -v1, v30, v29
	v_div_fmas_f32 v1, v1, v28, v30
	v_div_fixup_f32 v26, v1, v26, 1.0
	v_pk_mul_f32 v[24:25], v[24:25], v[26:27]
	s_nop 0
	v_pk_mul_f32 v[4:5], v[24:25], v[4:5]
	s_nop 0
	v_cvt_pk_bf16_f32 v1, v4, v5
	v_lshlrev_b32_e32 v4, 16, v6
	v_and_b32_e32 v5, 0xffff0000, v6
	v_rcp_f32_e32 v6, v2
	s_nop 0
	v_fma_f32 v16, -v2, v6, 1.0
	v_fmac_f32_e32 v6, v16, v6
	v_div_scale_f32 v16, vcc, 1.0, v13, 1.0
	v_mul_f32_e32 v17, v16, v6
	v_fma_f32 v20, -v2, v17, v16
	v_fmac_f32_e32 v17, v20, v6
	v_fma_f32 v2, -v2, v17, v16
	v_div_fmas_f32 v2, v2, v6, v17
	v_div_fixup_f32 v13, v2, v13, 1.0
	v_div_scale_f32 v2, s[20:21], v12, v12, 1.0
	v_rcp_f32_e32 v6, v2
	s_nop 0
	v_fma_f32 v16, -v2, v6, 1.0
	v_fmac_f32_e32 v6, v16, v6
	v_div_scale_f32 v16, vcc, 1.0, v12, 1.0
	v_mul_f32_e32 v17, v16, v6
	v_fma_f32 v20, -v2, v17, v16
	v_fmac_f32_e32 v17, v20, v6
	v_fma_f32 v2, -v2, v17, v16
	v_div_fmas_f32 v2, v2, v6, v17
	v_div_fixup_f32 v12, v2, v12, 1.0
	v_pk_mul_f32 v[8:9], v[8:9], v[12:13]
	s_nop 0
	v_pk_mul_f32 v[4:5], v[8:9], v[4:5]
	v_lshlrev_b32_e32 v8, 16, v3
	v_cvt_pk_bf16_f32 v2, v4, v5
	v_lshlrev_b32_e32 v4, 16, v7
	v_and_b32_e32 v5, 0xffff0000, v7
	v_pk_mul_f32 v[6:7], v[14:15], v[44:45]
	v_and_b32_e32 v9, 0xffff0000, v3
	v_pk_fma_f32 v[6:7], v[10:11], v[52:53], v[6:7]
	s_nop 0
	v_pk_fma_f32 v[6:7], v[18:19], v[8:9], v[6:7]
	s_nop 0
	v_pk_add_f32 v[6:7], v[6:7], v[22:23]
	s_nop 0
	v_mul_f32_e32 v3, 0xbfb8aa3b, v6
	v_exp_f32_e32 v8, v3
	v_mul_f32_e32 v3, 0xbfb8aa3b, v7
	v_exp_f32_e32 v9, v3
	s_nop 0
	v_pk_add_f32 v[8:9], v[8:9], 1.0 op_sel_hi:[1,0]
	s_nop 0
	v_div_scale_f32 v3, s[20:21], v9, v9, 1.0
	v_rcp_f32_e32 v10, v3
	s_nop 0
	v_fma_f32 v11, -v3, v10, 1.0
	v_fmac_f32_e32 v10, v11, v10
	v_div_scale_f32 v11, vcc, 1.0, v9, 1.0
	v_mul_f32_e32 v12, v11, v10
	v_fma_f32 v13, -v3, v12, v11
	v_fmac_f32_e32 v12, v13, v10
	v_fma_f32 v3, -v3, v12, v11
	v_div_fmas_f32 v3, v3, v10, v12
	v_div_fixup_f32 v9, v3, v9, 1.0
	v_div_scale_f32 v3, s[20:21], v8, v8, 1.0
	v_rcp_f32_e32 v10, v3
	s_mov_b64 s[20:21], 0x2bffff
	v_fma_f32 v11, -v3, v10, 1.0
	v_fmac_f32_e32 v10, v11, v10
	v_div_scale_f32 v11, vcc, 1.0, v8, 1.0
	v_mul_f32_e32 v12, v11, v10
	v_fma_f32 v13, -v3, v12, v11
	v_fmac_f32_e32 v12, v13, v10
	v_fma_f32 v3, -v3, v12, v11
	v_div_fmas_f32 v3, v3, v10, v12
	v_div_fixup_f32 v8, v3, v8, 1.0
	v_pk_mul_f32 v[6:7], v[6:7], v[8:9]
	s_nop 0
	v_pk_mul_f32 v[4:5], v[6:7], v[4:5]
	s_nop 0
	v_cvt_pk_bf16_f32 v3, v4, v5
	v_add_co_u32_e32 v4, vcc, 0x8000, v60
	s_nop 1
	v_addc_co_u32_e32 v5, vcc, 0, v61, vcc
	v_cmp_lt_u64_e32 vcc, s[20:21], v[72:73]
	s_or_b64 s[18:19], vcc, s[18:19]
	global_store_dwordx4 v[4:5], v[0:3], off offset:1024
	s_andn2_b64 exec, exec, s[18:19]
	s_cbranch_execz .LBB0_76
